# adds: sample-mLSTM item: normaliser-row load hoisted into the prologue, the vmcnt(0) store drain in front of its use removed
# baseline (speedup 1.0000x reference)
.LBB0_425:
	s_and_b64 vcc, exec, s[0:1]
	s_cbranch_vccz .LBB0_442
	s_and_b32 s25, s70, 0x3fc
	s_and_b32 s71, s70, 3
	s_or_b32 s0, s25, s71
	v_mov_b32_e32 v89, v0
	s_mov_b64 s[80:81], s[74:75]
	s_add_u32 s4, s80, 0x1b36e000
	s_addc_u32 s5, s81, 0
	s_add_i32 s38, s0, 0xffffff80
	s_lshl_b64 s[86:87], s[38:39], 18
	v_readfirstlane_b32 s85, v89
	s_add_u32 s0, s58, s86
	v_and_b32_e32 v3, 63, v89
	s_addc_u32 s1, s59, s87
	s_ashr_i32 s6, s85, 1
	s_and_b32 s82, s6, 0xffffffe0
	s_waitcnt vmcnt(17)
	v_lshlrev_b32_e32 v36, 4, v3
	v_mov_b32_e32 v37, v2
	v_lshl_add_u64 v[68:69], s[0:1], 0, v[36:37]
	s_ashr_i32 s83, s82, 31
	s_or_b32 s0, s82, 1
	s_lshl_b64 s[88:89], s[82:83], 10
	s_ashr_i32 s1, s0, 31
	v_lshl_add_u64 v[4:5], v[68:69], 0, s[88:89]
	s_lshl_b64 s[0:1], s[0:1], 10
	global_load_dwordx4 v[32:35], v[4:5], off nt
	v_lshl_add_u64 v[4:5], v[68:69], 0, s[0:1]
	s_or_b32 s0, s82, 2
	s_ashr_i32 s1, s0, 31
	s_lshl_b64 s[0:1], s[0:1], 10
	global_load_dwordx4 v[28:31], v[4:5], off nt
	v_lshl_add_u64 v[4:5], v[68:69], 0, s[0:1]
	s_or_b32 s0, s82, 3
	s_ashr_i32 s1, s0, 31
	s_lshl_b64 s[0:1], s[0:1], 10
	global_load_dwordx4 v[24:27], v[4:5], off nt
	v_lshl_add_u64 v[4:5], v[68:69], 0, s[0:1]
	s_or_b32 s0, s82, 4
	s_ashr_i32 s1, s0, 31
	s_lshl_b64 s[0:1], s[0:1], 10
	global_load_dwordx4 v[20:23], v[4:5], off nt
	v_lshl_add_u64 v[4:5], v[68:69], 0, s[0:1]
	s_or_b32 s0, s82, 5
	s_ashr_i32 s1, s0, 31
	s_lshl_b64 s[0:1], s[0:1], 10
	global_load_dwordx4 v[16:19], v[4:5], off nt
	v_lshl_add_u64 v[4:5], v[68:69], 0, s[0:1]
	s_or_b32 s0, s82, 6
	s_ashr_i32 s1, s0, 31
	s_lshl_b64 s[0:1], s[0:1], 10
	global_load_dwordx4 v[12:15], v[4:5], off nt
	v_lshl_add_u64 v[4:5], v[68:69], 0, s[0:1]
	s_or_b32 s0, s82, 7
	s_ashr_i32 s1, s0, 31
	s_lshl_b64 s[0:1], s[0:1], 10
	s_add_i32 s91, s25, 0x3f80
	s_lshl_b32 s6, s71, 9
	s_add_u32 s7, s80, s6
	global_load_dwordx4 v[8:11], v[4:5], off nt
	v_lshl_add_u64 v[4:5], v[68:69], 0, s[0:1]
	s_addc_u32 s8, s81, 0
	s_lshl_b64 s[0:1], s[82:83], 1
	v_and_b32_e32 v37, 31, v89
	s_add_u32 s0, s7, s0
	s_addc_u32 s1, s8, s1
	v_lshlrev_b32_e32 v38, 1, v37
	v_mov_b32_e32 v39, v2
	v_lshl_add_u64 v[38:39], s[0:1], 0, v[38:39]
	s_mov_b64 s[0:1], 0xcc6e000
	s_lshl_b32 s84, s71, 2
	s_waitcnt vmcnt(7)
	s_cmp_lt_u32 s85, 64
	s_cbranch_scc0 .Lb_nrow_skip
	s_lshl_b64 s[26:27], s[38:39], 10
	s_add_u32 s26, s60, s26
	s_addc_u32 s27, s61, s27
	v_lshlrev_b32_e32 v212, 4, v3
	global_load_dwordx4 v[208:211], v212, s[26:27]
.Lb_nrow_skip:
	v_lshl_add_u64 v[42:43], v[38:39], 0, s[0:1]
	s_add_u32 s0, s80, s84
	s_addc_u32 s1, s81, 0
	s_add_u32 s0, s0, 0x26a8000
	s_addc_u32 s1, s1, 0
	s_lshl_b32 s7, s91, 12
	s_add_u32 s7, s4, s7
	s_addc_u32 s9, s5, 0
	s_add_u32 s8, s7, s6
	s_addc_u32 s9, s9, 0
	v_lshlrev_b32_e32 v46, 3, v3
	global_load_dwordx4 v[4:7], v[4:5], off nt
	s_nop 0
	global_load_dwordx2 v[188:189], v46, s[8:9]
	global_load_dwordx2 v[194:195], v46, s[8:9] offset:2048
	s_lshl_b32 s8, s91, 11
	s_mov_b32 s9, s39
	s_lshl_b32 s7, s91, 5
	v_lshl_add_u64 v[196:197], v[42:43], 0, s[8:9]
	global_load_ushort v37, v[196:197], off
	v_mov_b32_e32 v204, s7
	s_add_i32 s7, s25, 0x3f81
	s_lshl_b32 s8, s7, 12
	s_add_u32 s8, s4, s8
	s_addc_u32 s9, s5, 0
	s_add_u32 s8, s8, s6
	s_addc_u32 s9, s9, 0
	global_load_dword v47, v204, s[0:1]
	global_load_dword v51, v204, s[0:1] offset:16
	s_nop 0
	global_load_dwordx2 v[190:191], v46, s[8:9]
	global_load_dwordx2 v[52:53], v46, s[8:9] offset:2048
	s_lshl_b32 s8, s7, 11
	s_mov_b32 s9, s39
	s_lshl_b32 s7, s7, 5
	v_lshl_add_u64 v[198:199], v[42:43], 0, s[8:9]
	global_load_ushort v44, v[198:199], off
	v_mov_b32_e32 v205, s7
	s_add_i32 s7, s25, 0x3f82
	s_lshl_b32 s8, s7, 12
	s_add_u32 s8, s4, s8
	s_addc_u32 s9, s5, 0
	s_add_u32 s8, s8, s6
	s_addc_u32 s9, s9, 0
	global_load_dword v50, v205, s[0:1]
	global_load_dword v56, v205, s[0:1] offset:16
	s_nop 0
	global_load_dwordx2 v[192:193], v46, s[8:9]
	global_load_dwordx2 v[40:41], v46, s[8:9] offset:2048
	s_lshl_b32 s8, s7, 11
	s_mov_b32 s9, s39
	s_lshl_b32 s7, s7, 5
	v_lshl_add_u64 v[200:201], v[42:43], 0, s[8:9]
	global_load_ushort v45, v[200:201], off
	v_mov_b32_e32 v206, s7
	s_add_i32 s7, s25, 0x3f83
	s_lshl_b32 s8, s7, 12
	s_add_u32 s4, s4, s8
	s_addc_u32 s5, s5, 0
	s_add_u32 s4, s4, s6
	s_addc_u32 s5, s5, 0
	global_load_dword v57, v206, s[0:1]
	global_load_dword v58, v206, s[0:1] offset:16
	global_load_dwordx2 v[54:55], v46, s[4:5]
	s_nop 0
	global_load_dwordx2 v[38:39], v46, s[4:5] offset:2048
	s_lshl_b32 s4, s7, 11
	s_mov_b32 s5, s39
	v_lshl_add_u64 v[42:43], v[42:43], 0, s[4:5]
	s_lshl_b32 s4, s7, 5
	global_load_ushort v42, v[42:43], off
	v_mov_b32_e32 v43, s4
	global_load_dword v49, v43, s[0:1]
	s_nop 0
	global_load_dword v43, v43, s[0:1] offset:16
	s_lshl_b64 s[0:1], s[38:39], 2
	s_add_u32 s0, s62, s0
	s_addc_u32 s1, s63, s1
	global_load_dword v207, v2, s[0:1]
	v_bfe_u32 v130, v89, 4, 2
	v_cmp_lt_i32_e32 vcc, v167, v161
	v_cmp_lt_u32_e64 s[10:11], 15, v3
	v_mov_b32_e32 v86, 0
	s_waitcnt vmcnt(20)
	v_lshlrev_b32_e32 v109, 16, v188
	v_and_b32_e32 v107, 0xffff0000, v188
	v_and_b32_e32 v71, 0xffff0000, v189
	v_lshlrev_b32_e32 v70, 16, v189
	s_waitcnt vmcnt(19)
	v_lshlrev_b32_e32 v80, 16, v195
	v_and_b32_e32 v81, 0xffff0000, v195
	v_lshlrev_b32_e32 v76, 16, v194
	v_and_b32_e32 v77, 0xffff0000, v194
	s_waitcnt vmcnt(15)
	v_lshlrev_b32_e32 v115, 16, v190
	v_and_b32_e32 v114, 0xffff0000, v190
	v_and_b32_e32 v73, 0xffff0000, v191
	v_lshlrev_b32_e32 v72, 16, v191
	s_waitcnt vmcnt(14)
	v_lshlrev_b32_e32 v78, 16, v52
	v_and_b32_e32 v79, 0xffff0000, v52
	v_lshlrev_b32_e32 v82, 16, v53
	v_and_b32_e32 v83, 0xffff0000, v53
	v_fma_f32 v60, v76, v115, 0
	v_fmac_f32_e32 v60, v77, v114
	v_fma_f32 v66, v78, v115, 0
	v_fmac_f32_e32 v66, v79, v114
	s_waitcnt vmcnt(10)
	v_lshlrev_b32_e32 v117, 16, v192
	v_and_b32_e32 v116, 0xffff0000, v192
	v_and_b32_e32 v75, 0xffff0000, v193
	v_lshlrev_b32_e32 v74, 16, v193
	v_cmp_eq_u32_e64 s[4:5], 1, v130
	v_fma_f32 v62, v76, v117, 0
	v_fmac_f32_e32 v62, v77, v116
	v_fma_f32 v87, v78, v117, 0
	v_fmac_f32_e32 v87, v79, v116
	v_cmp_eq_u32_e64 s[6:7], 2, v130
	v_cmp_eq_u32_e64 s[8:9], 3, v130
	s_waitcnt vmcnt(5)
	v_lshlrev_b32_e32 v119, 16, v54
	v_and_b32_e32 v118, 0xffff0000, v54
	v_and_b32_e32 v85, 0xffff0000, v55
	v_lshlrev_b32_e32 v84, 16, v55
	v_add_f32_e32 v55, v51, v56
	v_add_f32_e32 v56, v55, v58
	v_sub_f32_e32 v50, v50, v55
	s_waitcnt vmcnt(1)
	v_add_f32_e32 v46, v56, v43
	v_sub_f32_e32 v43, v47, v51
	v_sub_f32_e32 v48, v57, v56
	v_sub_f32_e32 v47, v49, v46
	v_max_f32_e32 v53, v43, v50
	v_add_f32_e32 v49, v51, v43
	v_max_f32_e32 v57, v53, v48
	v_add_f32_e32 v53, v55, v53
	v_max_f32_e32 v58, v57, v47
	v_add_f32_e32 v57, v56, v57
	v_fma_f32 v64, v76, v119, 0
	v_fmac_f32_e32 v64, v77, v118
	v_fma_f32 v88, v78, v119, 0
	v_fmac_f32_e32 v88, v79, v118
	v_pk_mul_f32 v[90:91], v[82:83], v[84:85]
	s_waitcnt vmcnt(0)
	v_add_f32_e32 v52, v51, v207
	v_max_f32_e32 v121, v52, v49
	v_add_f32_e32 v49, v55, v207
	v_max_f32_e32 v122, v49, v53
	v_add_f32_e32 v53, v56, v207
	v_max_f32_e32 v123, v53, v57
	v_sub_f32_e32 v51, v51, v121
	v_sub_f32_e32 v55, v55, v122
	v_cndmask_b32_e64 v51, v51, v55, s[4:5]
	v_sub_f32_e32 v55, v56, v123
	v_cndmask_b32_e32 v56, v160, v167, vcc
	v_cmp_lt_i32_e32 vcc, v166, v161
	v_lshlrev_b32_e32 v124, 2, v56
	v_add_f32_e32 v54, v207, v46
	v_cndmask_b32_e32 v56, v160, v166, vcc
	v_cmp_lt_i32_e32 vcc, v165, v161
	v_lshlrev_b32_e32 v125, 2, v56
	v_add_f32_e32 v57, v46, v58
	v_cndmask_b32_e32 v56, v160, v165, vcc
	v_cmp_lt_i32_e32 vcc, v164, v161
	v_lshlrev_b32_e32 v126, 2, v56
	v_fma_f32 v58, v76, v109, 0
	v_cndmask_b32_e32 v56, v160, v164, vcc
	v_cmp_lt_i32_e32 vcc, v163, v161
	v_lshlrev_b32_e32 v127, 2, v56
	v_max_f32_e32 v120, v54, v57
	v_cndmask_b32_e32 v56, v160, v163, vcc
	v_cmp_lt_i32_e32 vcc, v162, v161
	v_lshlrev_b32_e32 v128, 2, v56
	v_fmac_f32_e32 v58, v77, v107
	v_cndmask_b32_e32 v56, v160, v162, vcc
	v_lshlrev_b32_e32 v129, 2, v56
	v_pk_mul_f32 v[56:57], v[70:71], v[80:81]
	v_cndmask_b32_e64 v51, v51, v55, s[6:7]
	v_add_f32_e32 v56, v56, v58
	v_pk_mul_f32 v[58:59], v[80:81], v[72:73]
	v_add_f32_e32 v56, v57, v56
	v_add_f32_e32 v58, v58, v60
	v_pk_mul_f32 v[60:61], v[80:81], v[74:75]
	v_add_f32_e32 v58, v59, v58
	v_add_f32_e32 v60, v60, v62
	v_pk_mul_f32 v[62:63], v[80:81], v[84:85]
	v_add_f32_e32 v60, v61, v60
	v_add_f32_e32 v62, v62, v64
	v_pk_mul_f32 v[64:65], v[72:73], v[82:83]
	v_add_f32_e32 v62, v63, v62
	v_add_f32_e32 v64, v64, v66
	v_pk_mul_f32 v[66:67], v[82:83], v[74:75]
	v_add_f32_e32 v64, v65, v64
	v_add_f32_e32 v66, v66, v87
	v_add_f32_e32 v87, v90, v88
	v_add_f32_e32 v66, v67, v66
	v_add_f32_e32 v87, v91, v87
	ds_bpermute_b32 v57, v124, v56
	ds_bpermute_b32 v59, v124, v58
	ds_bpermute_b32 v61, v124, v60
	ds_bpermute_b32 v63, v124, v62
	ds_bpermute_b32 v65, v124, v64
	ds_bpermute_b32 v67, v124, v66
	ds_bpermute_b32 v88, v124, v87
	s_waitcnt lgkmcnt(6)
	v_add_f32_e32 v56, v56, v57
	s_waitcnt lgkmcnt(5)
	v_add_f32_e32 v58, v58, v59
	s_waitcnt lgkmcnt(4)
	v_add_f32_e32 v60, v60, v61
	s_waitcnt lgkmcnt(3)
	v_add_f32_e32 v62, v62, v63
	s_waitcnt lgkmcnt(2)
	v_add_f32_e32 v64, v64, v65
	s_waitcnt lgkmcnt(1)
	v_add_f32_e32 v66, v66, v67
	s_waitcnt lgkmcnt(0)
	v_add_f32_e32 v87, v87, v88
	ds_bpermute_b32 v57, v125, v56
	ds_bpermute_b32 v59, v125, v58
	ds_bpermute_b32 v61, v125, v60
	ds_bpermute_b32 v63, v125, v62
	ds_bpermute_b32 v65, v125, v64
	ds_bpermute_b32 v67, v125, v66
	ds_bpermute_b32 v88, v125, v87
	s_waitcnt lgkmcnt(6)
	v_add_f32_e32 v56, v56, v57
	s_waitcnt lgkmcnt(5)
	v_add_f32_e32 v58, v58, v59
	s_waitcnt lgkmcnt(4)
	v_add_f32_e32 v60, v60, v61
	s_waitcnt lgkmcnt(3)
	v_add_f32_e32 v62, v62, v63
	s_waitcnt lgkmcnt(2)
	v_add_f32_e32 v64, v64, v65
	s_waitcnt lgkmcnt(1)
	v_add_f32_e32 v66, v66, v67
	s_waitcnt lgkmcnt(0)
	v_add_f32_e32 v87, v87, v88
	ds_bpermute_b32 v57, v126, v56
	ds_bpermute_b32 v59, v126, v58
	ds_bpermute_b32 v61, v126, v60
	ds_bpermute_b32 v63, v126, v62
	ds_bpermute_b32 v65, v126, v64
	ds_bpermute_b32 v67, v126, v66
	ds_bpermute_b32 v88, v126, v87
	s_waitcnt lgkmcnt(6)
	v_add_f32_e32 v56, v56, v57
	s_waitcnt lgkmcnt(5)
	v_add_f32_e32 v58, v58, v59
	s_waitcnt lgkmcnt(4)
	v_add_f32_e32 v60, v60, v61
	s_waitcnt lgkmcnt(3)
	v_add_f32_e32 v62, v62, v63
	s_waitcnt lgkmcnt(2)
	v_add_f32_e32 v64, v64, v65
	s_waitcnt lgkmcnt(1)
	v_add_f32_e32 v66, v66, v67
	s_waitcnt lgkmcnt(0)
	v_add_f32_e32 v87, v87, v88
	ds_bpermute_b32 v57, v127, v56
	ds_bpermute_b32 v59, v127, v58
	ds_bpermute_b32 v61, v127, v60
	ds_bpermute_b32 v63, v127, v62
	ds_bpermute_b32 v65, v127, v64
	ds_bpermute_b32 v67, v127, v66
	ds_bpermute_b32 v88, v127, v87
	s_waitcnt lgkmcnt(6)
	v_add_f32_e32 v56, v56, v57
	s_waitcnt lgkmcnt(5)
	v_add_f32_e32 v58, v58, v59
	s_waitcnt lgkmcnt(4)
	v_add_f32_e32 v60, v60, v61
	s_waitcnt lgkmcnt(3)
	v_add_f32_e32 v62, v62, v63
	s_waitcnt lgkmcnt(2)
	v_add_f32_e32 v64, v64, v65
	s_waitcnt lgkmcnt(1)
	v_add_f32_e32 v66, v66, v67
	s_waitcnt lgkmcnt(0)
	v_add_f32_e32 v87, v87, v88
	ds_bpermute_b32 v57, v128, v56
	ds_bpermute_b32 v59, v128, v58
	ds_bpermute_b32 v61, v128, v60
	ds_bpermute_b32 v63, v128, v62
	ds_bpermute_b32 v65, v128, v64
	ds_bpermute_b32 v67, v128, v66
	ds_bpermute_b32 v88, v128, v87
	s_waitcnt lgkmcnt(6)
	v_add_f32_e32 v56, v56, v57
	s_waitcnt lgkmcnt(5)
	v_add_f32_e32 v58, v58, v59
	s_waitcnt lgkmcnt(4)
	v_add_f32_e32 v60, v60, v61
	s_waitcnt lgkmcnt(3)
	v_add_f32_e32 v62, v62, v63
	s_waitcnt lgkmcnt(2)
	v_add_f32_e32 v64, v64, v65
	s_waitcnt lgkmcnt(1)
	v_add_f32_e32 v66, v66, v67
	s_waitcnt lgkmcnt(0)
	v_add_f32_e32 v87, v87, v88
	ds_bpermute_b32 v57, v129, v56
	ds_bpermute_b32 v59, v129, v58
	ds_bpermute_b32 v61, v129, v60
	ds_bpermute_b32 v63, v129, v62
	ds_bpermute_b32 v65, v129, v64
	ds_bpermute_b32 v67, v129, v66
	ds_bpermute_b32 v90, v129, v87
	v_sub_f32_e32 v55, v46, v120
	v_cndmask_b32_e64 v51, v51, v55, s[8:9]
	v_cmp_gt_u32_e32 vcc, 16, v3
	v_mov_b32_e32 v88, 0
	s_and_saveexec_b64 s[0:1], s[10:11]
	s_cbranch_execz .LBB0_428
	s_waitcnt lgkmcnt(2)
	v_add_f32_e32 v64, v64, v65
	s_waitcnt lgkmcnt(1)
	v_add_f32_e32 v65, v66, v67
	v_add_f32_e32 v66, v50, v51
	v_mul_f32_e32 v66, 0x3fb8aa3b, v66
	v_exp_f32_e32 v66, v66
	s_waitcnt lgkmcnt(0)
	v_add_f32_e32 v67, v87, v90
	v_cndmask_b32_e64 v65, v67, v65, s[6:7]
	v_cndmask_b32_e64 v64, v65, v64, s[4:5]
	v_mul_f32_e32 v88, v66, v64

.LBB0_435:
	v_fma_f32 v99, v32, v109, 0
	v_fma_f32 v105, v32, v115, 0
	v_fma_f32 v140, v32, v117, 0
	v_fma_f32 v141, v32, v119, 0
	v_fmac_f32_e32 v99, v33, v107
	v_fmac_f32_e32 v105, v33, v114
	v_fmac_f32_e32 v140, v33, v116
	v_fmac_f32_e32 v141, v33, v118
	v_fmac_f32_e32 v99, v34, v70
	v_fmac_f32_e32 v105, v34, v72
	v_fmac_f32_e32 v140, v34, v74
	v_fmac_f32_e32 v141, v34, v84
	v_fmac_f32_e32 v99, v35, v71
	v_fmac_f32_e32 v105, v35, v73
	v_fmac_f32_e32 v140, v35, v75
	v_fmac_f32_e32 v141, v35, v85
	v_cndmask_b32_e64 v142, v140, v99, s[12:13]
	v_cndmask_b32_e64 v143, v141, v105, s[12:13]
	ds_bpermute_b32 v142, v129, v142
	ds_bpermute_b32 v143, v129, v143
	v_cndmask_b32_e64 v99, v99, v140, s[12:13]
	v_cndmask_b32_e64 v105, v105, v141, s[12:13]
	v_subrev_u32_e32 v141, 28, v137
	s_waitcnt lgkmcnt(1)
	v_add_f32_e32 v99, v99, v142
	s_waitcnt lgkmcnt(0)
	v_add_f32_e32 v105, v105, v143
	v_cndmask_b32_e64 v140, v99, v105, s[10:11]
	ds_bpermute_b32 v140, v128, v140
	v_cndmask_b32_e64 v99, v105, v99, s[10:11]
	ds_bpermute_b32 v142, v141, v134
	ds_bpermute_b32 v144, v141, v133
	ds_bpermute_b32 v147, v141, v136
	s_waitcnt lgkmcnt(3)
	v_add_f32_e32 v99, v99, v140
	ds_bpermute_b32 v105, v127, v99
	ds_bpermute_b32 v146, v141, v135
	s_waitcnt lgkmcnt(4)
	v_mul_f32_e32 v140, v102, v142
	s_waitcnt lgkmcnt(3)
	v_mul_f32_e32 v186, v100, v144
	v_pk_mul_f32 v[188:189], v[140:141], v[82:83] op_sel_hi:[0,1]
	s_waitcnt lgkmcnt(1)
	v_add_f32_e32 v105, v99, v105
	ds_bpermute_b32 v145, v126, v105
	v_pk_mul_f32 v[140:141], v[140:141], v[78:79] op_sel_hi:[0,1]
	v_pk_fma_f32 v[188:189], v[186:187], v[80:81], v[188:189] op_sel_hi:[0,1,1]
	v_pk_fma_f32 v[140:141], v[186:187], v[76:77], v[140:141] op_sel_hi:[0,1,1]
	v_mul_f32_e32 v168, v108, v147
	s_waitcnt lgkmcnt(0)
	v_pk_add_f32 v[186:187], v[104:105], v[144:145]
	ds_bpermute_b32 v159, v125, v187
	v_mul_f32_e32 v158, v88, v142
	v_mul_f32_e32 v142, v106, v146
	v_pk_fma_f32 v[32:33], v[110:111], v[32:33], v[140:141]
	v_mov_b32_e32 v99, v98
	v_pk_mul_f32 v[140:141], v[168:169], v[96:97] op_sel_hi:[0,1]
	v_pk_mul_f32 v[168:169], v[168:169], v[94:95] op_sel_hi:[0,1]
	v_pk_fma_f32 v[34:35], v[98:99], v[34:35], v[188:189]
	v_pk_fma_f32 v[168:169], v[142:143], v[90:91], v[168:169] op_sel_hi:[0,1,1]
	v_pk_fma_f32 v[140:141], v[142:143], v[92:93], v[140:141] op_sel_hi:[0,1,1]
	v_pk_add_f32 v[142:143], v[34:35], v[140:141]
	v_pk_add_f32 v[140:141], v[32:33], v[168:169]
	v_pk_mul_f32 v[32:33], v[104:105], v[144:145]
	s_movk_i32 s0, 0xf000
	v_mov_b32_e32 v33, v187
	s_waitcnt lgkmcnt(0)
	v_pk_add_f32 v[34:35], v[32:33], v[158:159]
	ds_bpermute_b32 v105, v124, v35
	v_add_co_u32_e32 v32, vcc, s0, v112
	s_cmp_lt_u32 s22, 16
	s_nop 0
	v_addc_co_u32_e32 v33, vcc, -1, v113, vcc
	global_store_dwordx4 v[32:33], v[140:143], off offset:-3072 nt
	s_cselect_b64 vcc, -1, 0
	s_nop 0
	v_mul_f32_e32 v140, v87, v147
	v_pk_fma_f32 v[140:141], v[86:87], v[146:147], v[140:141] op_sel_hi:[1,1,0]
	s_waitcnt lgkmcnt(0)
	v_mov_b32_e32 v141, v105
	v_pk_add_f32 v[34:35], v[34:35], v[140:141]
	v_fma_f32 v140, v28, v119, 0
	v_fmac_f32_e32 v34, v131, v35
	v_bitop3_b32 v35, s22, 15, v89 bitop3:0x48
	v_cndmask_b32_e32 v105, v34, v139, vcc
	v_cmp_eq_u32_e64 s[0:1], 0, v35
	v_fma_f32 v35, v28, v109, 0
	v_fmac_f32_e32 v35, v29, v107
	v_cndmask_b32_e64 v145, v139, v105, s[0:1]
	v_fma_f32 v105, v28, v115, 0
	v_fma_f32 v139, v28, v117, 0
	v_fmac_f32_e32 v105, v29, v114
	v_fmac_f32_e32 v139, v29, v116
	v_fmac_f32_e32 v140, v29, v118
	v_fmac_f32_e32 v35, v30, v70
	v_fmac_f32_e32 v105, v30, v72
	v_fmac_f32_e32 v139, v30, v74
	v_fmac_f32_e32 v140, v30, v84
	v_fmac_f32_e32 v35, v31, v71
	v_fmac_f32_e32 v105, v31, v73
	v_fmac_f32_e32 v139, v31, v75
	v_fmac_f32_e32 v140, v31, v85
	v_cndmask_b32_e64 v141, v139, v35, s[12:13]
	v_cndmask_b32_e64 v142, v140, v105, s[12:13]
	ds_bpermute_b32 v141, v129, v141
	ds_bpermute_b32 v142, v129, v142
	s_and_b64 s[0:1], s[0:1], vcc
	v_cndmask_b32_e64 v151, v138, v34, s[0:1]
	v_cndmask_b32_e64 v34, v35, v139, s[12:13]
	v_cndmask_b32_e64 v35, v105, v140, s[12:13]
	s_waitcnt lgkmcnt(1)
	v_add_f32_e32 v34, v34, v141
	s_waitcnt lgkmcnt(0)
	v_add_f32_e32 v35, v35, v142
	v_cndmask_b32_e64 v105, v34, v35, s[10:11]
	ds_bpermute_b32 v105, v128, v105
	v_cndmask_b32_e64 v34, v35, v34, s[10:11]
	v_subrev_u32_e32 v139, 24, v137
	ds_bpermute_b32 v141, v139, v134
	ds_bpermute_b32 v138, v139, v135
	s_waitcnt lgkmcnt(2)
	v_add_f32_e32 v35, v34, v105
	ds_bpermute_b32 v105, v127, v35
	ds_bpermute_b32 v34, v139, v133
	s_waitcnt lgkmcnt(3)
	v_mul_f32_e32 v140, v102, v141
	v_mul_f32_e32 v142, v88, v141
	v_pk_mul_f32 v[168:169], v[140:141], v[82:83] op_sel_hi:[0,1]
	s_waitcnt lgkmcnt(1)
	v_add_f32_e32 v105, v35, v105
	ds_bpermute_b32 v35, v126, v105
	s_waitcnt lgkmcnt(1)
	v_mul_f32_e32 v158, v100, v34
	v_pk_mul_f32 v[140:141], v[140:141], v[78:79] op_sel_hi:[0,1]
	v_pk_fma_f32 v[168:169], v[158:159], v[80:81], v[168:169] op_sel_hi:[0,1,1]
	v_pk_fma_f32 v[140:141], v[158:159], v[76:77], v[140:141] op_sel_hi:[0,1,1]
	s_waitcnt lgkmcnt(0)
	v_pk_add_f32 v[158:159], v[104:105], v[34:35]
	ds_bpermute_b32 v139, v139, v136
	ds_bpermute_b32 v143, v125, v159
	v_pk_mul_f32 v[34:35], v[104:105], v[34:35]
	v_mul_f32_e32 v144, v106, v138
	v_mov_b32_e32 v35, v159
	s_waitcnt lgkmcnt(1)
	v_mul_f32_e32 v146, v108, v139
	s_waitcnt lgkmcnt(0)
	v_pk_add_f32 v[34:35], v[34:35], v[142:143]
	v_pk_fma_f32 v[28:29], v[110:111], v[28:29], v[140:141]
	v_pk_mul_f32 v[140:141], v[146:147], v[96:97] op_sel_hi:[0,1]
	v_pk_mul_f32 v[146:147], v[146:147], v[94:95] op_sel_hi:[0,1]
	ds_bpermute_b32 v105, v124, v35
	v_pk_fma_f32 v[30:31], v[98:99], v[30:31], v[168:169]
	v_pk_fma_f32 v[146:147], v[144:145], v[90:91], v[146:147] op_sel_hi:[0,1,1]
	v_pk_fma_f32 v[140:141], v[144:145], v[92:93], v[140:141] op_sel_hi:[0,1,1]
	v_pk_add_f32 v[30:31], v[30:31], v[140:141]
	v_pk_add_f32 v[28:29], v[28:29], v[146:147]
	global_store_dwordx4 v[32:33], v[28:31], off offset:-2048 nt
	s_add_i32 s0, s21, -2
	s_nop 0
	v_mul_f32_e32 v28, v87, v139
	v_pk_fma_f32 v[28:29], v[86:87], v[138:139], v[28:29] op_sel_hi:[1,1,0]
	v_fma_f32 v31, v24, v117, 0
	s_waitcnt lgkmcnt(0)
	v_mov_b32_e32 v29, v105
	v_pk_add_f32 v[28:29], v[34:35], v[28:29]
	v_fma_f32 v34, v24, v119, 0
	v_fmac_f32_e32 v28, v131, v29
	v_bitop3_b32 v29, s0, 15, v89 bitop3:0x48
	v_cndmask_b32_e32 v30, v28, v145, vcc
	v_cmp_eq_u32_e64 s[0:1], 0, v29
	v_fma_f32 v29, v24, v109, 0
	v_fmac_f32_e32 v29, v25, v107
	v_cndmask_b32_e64 v141, v145, v30, s[0:1]
	v_fma_f32 v30, v24, v115, 0
	v_fmac_f32_e32 v30, v25, v114
	v_fmac_f32_e32 v31, v25, v116
	v_fmac_f32_e32 v34, v25, v118
	v_fmac_f32_e32 v29, v26, v70
	v_fmac_f32_e32 v30, v26, v72
	v_fmac_f32_e32 v31, v26, v74
	v_fmac_f32_e32 v34, v26, v84
	v_fmac_f32_e32 v29, v27, v71
	v_fmac_f32_e32 v30, v27, v73
	v_fmac_f32_e32 v31, v27, v75
	v_fmac_f32_e32 v34, v27, v85
	v_cndmask_b32_e64 v35, v31, v29, s[12:13]
	v_cndmask_b32_e64 v105, v34, v30, s[12:13]
	ds_bpermute_b32 v35, v129, v35
	ds_bpermute_b32 v105, v129, v105
	s_and_b64 s[0:1], s[0:1], vcc
	v_cndmask_b32_e64 v151, v151, v28, s[0:1]
	v_cndmask_b32_e64 v28, v29, v31, s[12:13]
	v_cndmask_b32_e64 v29, v30, v34, s[12:13]
	s_waitcnt lgkmcnt(1)
	v_add_f32_e32 v28, v28, v35
	s_waitcnt lgkmcnt(0)
	v_add_f32_e32 v29, v29, v105
	v_cndmask_b32_e64 v30, v28, v29, s[10:11]
	ds_bpermute_b32 v30, v128, v30
	v_cndmask_b32_e64 v28, v29, v28, s[10:11]
	v_subrev_u32_e32 v31, 20, v137
	ds_bpermute_b32 v35, v31, v134
	s_add_i32 s0, s21, -1
	s_waitcnt lgkmcnt(1)
	v_add_f32_e32 v29, v28, v30
	ds_bpermute_b32 v105, v127, v29
	ds_bpermute_b32 v28, v31, v133
	s_waitcnt lgkmcnt(2)
	v_mul_f32_e32 v34, v102, v35
	ds_bpermute_b32 v30, v31, v135
	ds_bpermute_b32 v31, v31, v136
	s_waitcnt lgkmcnt(3)
	v_add_f32_e32 v105, v29, v105
	ds_bpermute_b32 v29, v126, v105
	v_mul_f32_e32 v138, v88, v35
	s_waitcnt lgkmcnt(3)
	v_mul_f32_e32 v144, v100, v28
	v_pk_mul_f32 v[146:147], v[34:35], v[82:83] op_sel_hi:[0,1]
	v_pk_mul_f32 v[34:35], v[34:35], v[78:79] op_sel_hi:[0,1]
	v_pk_fma_f32 v[146:147], v[144:145], v[80:81], v[146:147] op_sel_hi:[0,1,1]
	v_pk_fma_f32 v[34:35], v[144:145], v[76:77], v[34:35] op_sel_hi:[0,1,1]
	s_waitcnt lgkmcnt(0)
	v_pk_add_f32 v[144:145], v[104:105], v[28:29]
	ds_bpermute_b32 v139, v125, v145
	v_mul_f32_e32 v142, v108, v31
	v_pk_mul_f32 v[28:29], v[104:105], v[28:29]
	v_mul_f32_e32 v140, v106, v30
	v_pk_fma_f32 v[24:25], v[110:111], v[24:25], v[34:35]
	v_pk_mul_f32 v[34:35], v[142:143], v[96:97] op_sel_hi:[0,1]
	v_mov_b32_e32 v29, v145
	v_pk_fma_f32 v[26:27], v[98:99], v[26:27], v[146:147]
	v_pk_fma_f32 v[34:35], v[140:141], v[92:93], v[34:35] op_sel_hi:[0,1,1]
	s_waitcnt lgkmcnt(0)
	v_pk_add_f32 v[28:29], v[28:29], v[138:139]
	v_pk_mul_f32 v[142:143], v[142:143], v[94:95] op_sel_hi:[0,1]
	v_pk_add_f32 v[26:27], v[26:27], v[34:35]
	ds_bpermute_b32 v34, v124, v29
	v_pk_fma_f32 v[142:143], v[140:141], v[90:91], v[142:143] op_sel_hi:[0,1,1]
	v_pk_add_f32 v[24:25], v[24:25], v[142:143]
	global_store_dwordx4 v[32:33], v[24:27], off offset:-1024 nt
	s_nop 1
	v_mul_f32_e32 v24, v87, v31
	v_pk_fma_f32 v[24:25], v[86:87], v[30:31], v[24:25] op_sel_hi:[1,1,0]
	v_fma_f32 v27, v20, v109, 0
	s_waitcnt lgkmcnt(0)
	v_mov_b32_e32 v25, v34
	v_pk_add_f32 v[24:25], v[28:29], v[24:25]
	v_fma_f32 v28, v20, v115, 0
	v_fma_f32 v29, v20, v117, 0
	v_fma_f32 v30, v20, v119, 0
	v_fmac_f32_e32 v27, v21, v107
	v_fmac_f32_e32 v28, v21, v114
	v_fmac_f32_e32 v29, v21, v116
	v_fmac_f32_e32 v30, v21, v118
	v_fmac_f32_e32 v27, v22, v70
	v_fmac_f32_e32 v28, v22, v72
	v_fmac_f32_e32 v29, v22, v74
	v_fmac_f32_e32 v30, v22, v84
	v_fmac_f32_e32 v27, v23, v71
	v_fmac_f32_e32 v28, v23, v73
	v_fmac_f32_e32 v29, v23, v75
	v_fmac_f32_e32 v30, v23, v85
	v_cndmask_b32_e64 v31, v29, v27, s[12:13]
	v_cndmask_b32_e64 v32, v30, v28, s[12:13]
	ds_bpermute_b32 v31, v129, v31
	ds_bpermute_b32 v32, v129, v32
	v_fmac_f32_e32 v24, v131, v25
	v_bitop3_b32 v25, s0, 15, v89 bitop3:0x48
	v_cndmask_b32_e32 v26, v24, v141, vcc
	v_cmp_eq_u32_e64 s[0:1], 0, v25
	v_cndmask_b32_e64 v25, v27, v29, s[12:13]
	s_waitcnt lgkmcnt(1)
	v_add_f32_e32 v25, v25, v31
	v_cndmask_b32_e64 v33, v141, v26, s[0:1]
	v_cndmask_b32_e64 v26, v28, v30, s[12:13]
	s_waitcnt lgkmcnt(0)
	v_add_f32_e32 v26, v26, v32
	v_cndmask_b32_e64 v27, v25, v26, s[10:11]
	ds_bpermute_b32 v27, v128, v27
	s_and_b64 s[0:1], s[0:1], vcc
	v_cndmask_b32_e64 v142, v151, v24, s[0:1]
	v_cndmask_b32_e64 v24, v26, v25, s[10:11]
	v_add_u32_e32 v28, -16, v137
	s_waitcnt lgkmcnt(0)
	v_add_f32_e32 v25, v24, v27
	ds_bpermute_b32 v30, v127, v25
	ds_bpermute_b32 v29, v28, v134
	ds_bpermute_b32 v24, v28, v133
	ds_bpermute_b32 v26, v28, v135
	ds_bpermute_b32 v27, v28, v136
	s_waitcnt lgkmcnt(4)
	v_add_f32_e32 v105, v25, v30
	ds_bpermute_b32 v25, v126, v105
	s_waitcnt lgkmcnt(4)
	v_mul_f32_e32 v28, v102, v29
	v_mul_f32_e32 v30, v88, v29
	s_waitcnt lgkmcnt(3)
	v_mul_f32_e32 v138, v100, v24
	v_pk_mul_f32 v[140:141], v[28:29], v[82:83] op_sel_hi:[0,1]
	v_pk_mul_f32 v[28:29], v[28:29], v[78:79] op_sel_hi:[0,1]
	v_pk_fma_f32 v[140:141], v[138:139], v[80:81], v[140:141] op_sel_hi:[0,1,1]
	v_pk_fma_f32 v[28:29], v[138:139], v[76:77], v[28:29] op_sel_hi:[0,1,1]
	s_waitcnt lgkmcnt(0)
	v_pk_add_f32 v[138:139], v[104:105], v[24:25]
	ds_bpermute_b32 v31, v125, v139
	v_mul_f32_e32 v34, v108, v27
	v_pk_mul_f32 v[24:25], v[104:105], v[24:25]
	v_mul_f32_e32 v32, v106, v26
	v_pk_fma_f32 v[20:21], v[110:111], v[20:21], v[28:29]
	v_pk_mul_f32 v[28:29], v[34:35], v[96:97] op_sel_hi:[0,1]
	v_mov_b32_e32 v25, v139
	v_pk_fma_f32 v[22:23], v[98:99], v[22:23], v[140:141]
	v_pk_fma_f32 v[28:29], v[32:33], v[92:93], v[28:29] op_sel_hi:[0,1,1]
	s_waitcnt lgkmcnt(0)
	v_pk_add_f32 v[24:25], v[24:25], v[30:31]
	v_pk_mul_f32 v[34:35], v[34:35], v[94:95] op_sel_hi:[0,1]
	v_pk_add_f32 v[22:23], v[22:23], v[28:29]
	ds_bpermute_b32 v28, v124, v25
	v_pk_fma_f32 v[34:35], v[32:33], v[90:91], v[34:35] op_sel_hi:[0,1,1]
	v_pk_add_f32 v[20:21], v[20:21], v[34:35]
	global_store_dwordx4 v[112:113], v[20:23], off offset:-4096 nt
	s_nop 1
	v_mul_f32_e32 v20, v87, v27
	v_pk_fma_f32 v[20:21], v[86:87], v[26:27], v[20:21] op_sel_hi:[1,1,0]
	v_fma_f32 v23, v16, v117, 0
	s_waitcnt lgkmcnt(0)
	v_mov_b32_e32 v21, v28
	v_pk_add_f32 v[20:21], v[24:25], v[20:21]
	v_fma_f32 v24, v16, v119, 0
	v_fmac_f32_e32 v20, v131, v21
	v_bitop3_b32 v21, s21, 15, v89 bitop3:0x48
	v_cndmask_b32_e32 v22, v20, v33, vcc
	v_cmp_eq_u32_e64 s[0:1], 0, v21
	v_fma_f32 v21, v16, v109, 0
	v_fmac_f32_e32 v21, v17, v107
	v_cndmask_b32_e64 v29, v33, v22, s[0:1]
	v_fma_f32 v22, v16, v115, 0
	v_fmac_f32_e32 v22, v17, v114
	v_fmac_f32_e32 v23, v17, v116
	v_fmac_f32_e32 v24, v17, v118
	v_fmac_f32_e32 v21, v18, v70
	v_fmac_f32_e32 v22, v18, v72
	v_fmac_f32_e32 v23, v18, v74
	v_fmac_f32_e32 v24, v18, v84
	v_fmac_f32_e32 v21, v19, v71
	v_fmac_f32_e32 v22, v19, v73
	v_fmac_f32_e32 v23, v19, v75
	v_fmac_f32_e32 v24, v19, v85
	v_cndmask_b32_e64 v25, v23, v21, s[12:13]
	v_cndmask_b32_e64 v26, v24, v22, s[12:13]
	ds_bpermute_b32 v25, v129, v25
	ds_bpermute_b32 v26, v129, v26
	s_and_b64 s[0:1], s[0:1], vcc
	v_cndmask_b32_e64 v138, v142, v20, s[0:1]
	v_cndmask_b32_e64 v20, v21, v23, s[12:13]
	v_cndmask_b32_e64 v21, v22, v24, s[12:13]
	s_waitcnt lgkmcnt(1)
	v_add_f32_e32 v20, v20, v25
	s_waitcnt lgkmcnt(0)
	v_add_f32_e32 v21, v21, v26
	v_cndmask_b32_e64 v22, v20, v21, s[10:11]
	ds_bpermute_b32 v22, v128, v22
	v_cndmask_b32_e64 v20, v21, v20, s[10:11]
	v_add_u32_e32 v23, -12, v137
	ds_bpermute_b32 v25, v23, v134
	s_add_i32 s0, s21, 1
	s_waitcnt lgkmcnt(1)
	v_add_f32_e32 v21, v20, v22
	ds_bpermute_b32 v26, v127, v21
	ds_bpermute_b32 v20, v23, v133
	s_waitcnt lgkmcnt(2)
	v_mul_f32_e32 v24, v102, v25
	ds_bpermute_b32 v22, v23, v135
	ds_bpermute_b32 v23, v23, v136
	s_waitcnt lgkmcnt(3)
	v_add_f32_e32 v105, v21, v26
	ds_bpermute_b32 v21, v126, v105
	v_mul_f32_e32 v26, v88, v25
	s_waitcnt lgkmcnt(3)
	v_mul_f32_e32 v32, v100, v20
	v_pk_mul_f32 v[34:35], v[24:25], v[82:83] op_sel_hi:[0,1]
	v_pk_mul_f32 v[24:25], v[24:25], v[78:79] op_sel_hi:[0,1]
	v_pk_fma_f32 v[34:35], v[32:33], v[80:81], v[34:35] op_sel_hi:[0,1,1]
	v_pk_fma_f32 v[24:25], v[32:33], v[76:77], v[24:25] op_sel_hi:[0,1,1]
	s_waitcnt lgkmcnt(0)
	v_pk_add_f32 v[32:33], v[104:105], v[20:21]
	ds_bpermute_b32 v27, v125, v33
	v_mul_f32_e32 v30, v108, v23
	v_pk_mul_f32 v[20:21], v[104:105], v[20:21]
	v_mul_f32_e32 v28, v106, v22
	v_pk_fma_f32 v[16:17], v[110:111], v[16:17], v[24:25]
	v_pk_mul_f32 v[24:25], v[30:31], v[96:97] op_sel_hi:[0,1]
	v_mov_b32_e32 v21, v33
	v_pk_fma_f32 v[18:19], v[98:99], v[18:19], v[34:35]
	v_pk_fma_f32 v[24:25], v[28:29], v[92:93], v[24:25] op_sel_hi:[0,1,1]
	s_waitcnt lgkmcnt(0)
	v_pk_add_f32 v[20:21], v[20:21], v[26:27]
	v_pk_mul_f32 v[30:31], v[30:31], v[94:95] op_sel_hi:[0,1]
	v_pk_add_f32 v[18:19], v[18:19], v[24:25]
	ds_bpermute_b32 v24, v124, v21
	v_pk_fma_f32 v[30:31], v[28:29], v[90:91], v[30:31] op_sel_hi:[0,1,1]
	v_pk_add_f32 v[16:17], v[16:17], v[30:31]
	global_store_dwordx4 v[112:113], v[16:19], off offset:-3072 nt
	s_nop 1
	v_mul_f32_e32 v16, v87, v23
	v_pk_fma_f32 v[16:17], v[86:87], v[22:23], v[16:17] op_sel_hi:[1,1,0]
	v_fma_f32 v19, v12, v117, 0
	s_waitcnt lgkmcnt(0)
	v_mov_b32_e32 v17, v24
	v_pk_add_f32 v[16:17], v[20:21], v[16:17]
	v_fma_f32 v20, v12, v119, 0
	v_fmac_f32_e32 v16, v131, v17
	v_bitop3_b32 v17, s0, 15, v89 bitop3:0x48
	v_cndmask_b32_e32 v18, v16, v29, vcc
	v_cmp_eq_u32_e64 s[0:1], 0, v17
	v_fma_f32 v17, v12, v109, 0
	v_fmac_f32_e32 v17, v13, v107
	v_cndmask_b32_e64 v25, v29, v18, s[0:1]
	v_fma_f32 v18, v12, v115, 0
	v_fmac_f32_e32 v18, v13, v114
	v_fmac_f32_e32 v19, v13, v116
	v_fmac_f32_e32 v20, v13, v118
	v_fmac_f32_e32 v17, v14, v70
	v_fmac_f32_e32 v18, v14, v72
	v_fmac_f32_e32 v19, v14, v74
	v_fmac_f32_e32 v20, v14, v84
	v_fmac_f32_e32 v17, v15, v71
	v_fmac_f32_e32 v18, v15, v73
	v_fmac_f32_e32 v19, v15, v75
	v_fmac_f32_e32 v20, v15, v85
	v_cndmask_b32_e64 v21, v19, v17, s[12:13]
	v_cndmask_b32_e64 v22, v20, v18, s[12:13]
	ds_bpermute_b32 v21, v129, v21
	ds_bpermute_b32 v22, v129, v22
	s_and_b64 s[0:1], s[0:1], vcc
	v_cndmask_b32_e64 v32, v138, v16, s[0:1]
	v_cndmask_b32_e64 v16, v17, v19, s[12:13]
	v_cndmask_b32_e64 v17, v18, v20, s[12:13]
	s_waitcnt lgkmcnt(1)
	v_add_f32_e32 v16, v16, v21
	s_waitcnt lgkmcnt(0)
	v_add_f32_e32 v17, v17, v22
	v_cndmask_b32_e64 v18, v16, v17, s[10:11]
	ds_bpermute_b32 v18, v128, v18
	v_cndmask_b32_e64 v16, v17, v16, s[10:11]
	v_add_u32_e32 v19, -8, v137
	ds_bpermute_b32 v21, v19, v134
	s_add_i32 s0, s21, 2
	s_waitcnt lgkmcnt(1)
	v_add_f32_e32 v17, v16, v18
	ds_bpermute_b32 v22, v127, v17
	ds_bpermute_b32 v16, v19, v133
	s_waitcnt lgkmcnt(2)
	v_mul_f32_e32 v20, v102, v21
	ds_bpermute_b32 v18, v19, v135
	ds_bpermute_b32 v19, v19, v136
	s_waitcnt lgkmcnt(3)
	v_add_f32_e32 v105, v17, v22
	ds_bpermute_b32 v17, v126, v105
	v_mul_f32_e32 v22, v88, v21
	s_waitcnt lgkmcnt(3)
	v_mul_f32_e32 v28, v100, v16
	v_pk_mul_f32 v[30:31], v[20:21], v[82:83] op_sel_hi:[0,1]
	v_pk_mul_f32 v[20:21], v[20:21], v[78:79] op_sel_hi:[0,1]
	v_pk_fma_f32 v[30:31], v[28:29], v[80:81], v[30:31] op_sel_hi:[0,1,1]
	v_pk_fma_f32 v[20:21], v[28:29], v[76:77], v[20:21] op_sel_hi:[0,1,1]
	s_waitcnt lgkmcnt(0)
	v_pk_add_f32 v[28:29], v[104:105], v[16:17]
	ds_bpermute_b32 v23, v125, v29
	v_mul_f32_e32 v26, v108, v19
	v_pk_mul_f32 v[16:17], v[104:105], v[16:17]
	v_mul_f32_e32 v24, v106, v18
	v_pk_fma_f32 v[12:13], v[110:111], v[12:13], v[20:21]
	v_pk_mul_f32 v[20:21], v[26:27], v[96:97] op_sel_hi:[0,1]
	v_mov_b32_e32 v17, v29
	v_pk_fma_f32 v[14:15], v[98:99], v[14:15], v[30:31]
	v_pk_fma_f32 v[20:21], v[24:25], v[92:93], v[20:21] op_sel_hi:[0,1,1]
	s_waitcnt lgkmcnt(0)
	v_pk_add_f32 v[16:17], v[16:17], v[22:23]
	v_pk_mul_f32 v[26:27], v[26:27], v[94:95] op_sel_hi:[0,1]
	v_pk_add_f32 v[14:15], v[14:15], v[20:21]
	ds_bpermute_b32 v20, v124, v17
	v_pk_fma_f32 v[26:27], v[24:25], v[90:91], v[26:27] op_sel_hi:[0,1,1]
	v_pk_add_f32 v[12:13], v[12:13], v[26:27]
	global_store_dwordx4 v[112:113], v[12:15], off offset:-2048 nt
	s_nop 1
	v_mul_f32_e32 v12, v87, v19
	v_pk_fma_f32 v[12:13], v[86:87], v[18:19], v[12:13] op_sel_hi:[1,1,0]
	v_fma_f32 v15, v8, v117, 0
	s_waitcnt lgkmcnt(0)
	v_mov_b32_e32 v13, v20
	v_pk_add_f32 v[12:13], v[16:17], v[12:13]
	v_fma_f32 v16, v8, v119, 0
	v_fmac_f32_e32 v12, v131, v13
	v_bitop3_b32 v13, s0, 15, v89 bitop3:0x48
	v_cndmask_b32_e32 v14, v12, v25, vcc
	v_cmp_eq_u32_e64 s[0:1], 0, v13
	v_fma_f32 v13, v8, v109, 0
	v_fmac_f32_e32 v13, v9, v107
	v_cndmask_b32_e64 v21, v25, v14, s[0:1]
	v_fma_f32 v14, v8, v115, 0
	v_fmac_f32_e32 v14, v9, v114
	v_fmac_f32_e32 v15, v9, v116
	v_fmac_f32_e32 v16, v9, v118
	v_fmac_f32_e32 v13, v10, v70
	v_fmac_f32_e32 v14, v10, v72
	v_fmac_f32_e32 v15, v10, v74
	v_fmac_f32_e32 v16, v10, v84
	v_fmac_f32_e32 v13, v11, v71
	v_fmac_f32_e32 v14, v11, v73
	v_fmac_f32_e32 v15, v11, v75
	v_fmac_f32_e32 v16, v11, v85
	v_cndmask_b32_e64 v17, v15, v13, s[12:13]
	v_cndmask_b32_e64 v18, v16, v14, s[12:13]
	ds_bpermute_b32 v17, v129, v17
	ds_bpermute_b32 v18, v129, v18
	s_and_b64 s[0:1], s[0:1], vcc
	v_cndmask_b32_e64 v28, v32, v12, s[0:1]
	v_cndmask_b32_e64 v12, v13, v15, s[12:13]
	v_cndmask_b32_e64 v13, v14, v16, s[12:13]
	s_waitcnt lgkmcnt(1)
	v_add_f32_e32 v12, v12, v17
	s_waitcnt lgkmcnt(0)
	v_add_f32_e32 v13, v13, v18
	v_cndmask_b32_e64 v14, v12, v13, s[10:11]
	ds_bpermute_b32 v14, v128, v14
	v_cndmask_b32_e64 v12, v13, v12, s[10:11]
	v_add_u32_e32 v15, -4, v137
	ds_bpermute_b32 v17, v15, v134
	s_add_i32 s0, s21, 3
	s_waitcnt lgkmcnt(1)
	v_add_f32_e32 v13, v12, v14
	ds_bpermute_b32 v18, v127, v13
	ds_bpermute_b32 v12, v15, v133
	s_waitcnt lgkmcnt(2)
	v_mul_f32_e32 v16, v102, v17
	ds_bpermute_b32 v14, v15, v135
	ds_bpermute_b32 v15, v15, v136
	s_waitcnt lgkmcnt(3)
	v_add_f32_e32 v105, v13, v18
	ds_bpermute_b32 v13, v126, v105
	v_mul_f32_e32 v18, v88, v17
	s_waitcnt lgkmcnt(3)
	v_mul_f32_e32 v24, v100, v12
	v_pk_mul_f32 v[26:27], v[16:17], v[82:83] op_sel_hi:[0,1]
	v_pk_mul_f32 v[16:17], v[16:17], v[78:79] op_sel_hi:[0,1]
	v_pk_fma_f32 v[26:27], v[24:25], v[80:81], v[26:27] op_sel_hi:[0,1,1]
	v_pk_fma_f32 v[16:17], v[24:25], v[76:77], v[16:17] op_sel_hi:[0,1,1]
	s_waitcnt lgkmcnt(0)
	v_pk_add_f32 v[24:25], v[104:105], v[12:13]
	ds_bpermute_b32 v19, v125, v25
	v_mul_f32_e32 v22, v108, v15
	v_pk_mul_f32 v[12:13], v[104:105], v[12:13]
	v_mul_f32_e32 v20, v106, v14
	v_pk_fma_f32 v[8:9], v[110:111], v[8:9], v[16:17]
	v_pk_mul_f32 v[16:17], v[22:23], v[96:97] op_sel_hi:[0,1]
	v_mov_b32_e32 v13, v25
	v_pk_fma_f32 v[10:11], v[98:99], v[10:11], v[26:27]
	v_pk_fma_f32 v[16:17], v[20:21], v[92:93], v[16:17] op_sel_hi:[0,1,1]
	s_waitcnt lgkmcnt(0)
	v_pk_add_f32 v[12:13], v[12:13], v[18:19]
	v_pk_mul_f32 v[22:23], v[22:23], v[94:95] op_sel_hi:[0,1]
	v_pk_add_f32 v[10:11], v[10:11], v[16:17]
	ds_bpermute_b32 v16, v124, v13
	v_pk_fma_f32 v[22:23], v[20:21], v[90:91], v[22:23] op_sel_hi:[0,1,1]
	v_pk_add_f32 v[8:9], v[8:9], v[22:23]
	global_store_dwordx4 v[112:113], v[8:11], off offset:-1024 nt
	s_nop 1
	v_mul_f32_e32 v8, v87, v15
	v_pk_fma_f32 v[8:9], v[86:87], v[14:15], v[8:9] op_sel_hi:[1,1,0]
	v_pk_mul_f32 v[10:11], v[6:7], v[70:71]
	s_waitcnt lgkmcnt(0)
	v_mov_b32_e32 v9, v16
	v_pk_add_f32 v[8:9], v[12:13], v[8:9]
	v_fma_f32 v13, v4, v109, 0
	v_fmac_f32_e32 v13, v5, v107
	v_fma_f32 v14, v4, v115, 0
	v_add_f32_e32 v10, v10, v13
	v_fmac_f32_e32 v14, v5, v114
	v_add_f32_e32 v13, v11, v10
	v_pk_mul_f32 v[10:11], v[6:7], v[72:73]
	v_fma_f32 v15, v4, v117, 0
	v_add_f32_e32 v10, v10, v14
	v_fmac_f32_e32 v15, v5, v116
	v_add_f32_e32 v14, v11, v10
	v_pk_mul_f32 v[10:11], v[6:7], v[74:75]
	v_fma_f32 v16, v4, v119, 0
	v_add_f32_e32 v10, v10, v15
	v_fmac_f32_e32 v16, v5, v118
	v_add_f32_e32 v15, v11, v10
	v_pk_mul_f32 v[10:11], v[6:7], v[84:85]
	v_fmac_f32_e32 v8, v131, v9
	v_add_f32_e32 v10, v10, v16
	v_add_f32_e32 v10, v11, v10
	v_cndmask_b32_e64 v11, v15, v13, s[12:13]
	v_cndmask_b32_e64 v16, v10, v14, s[12:13]
	ds_bpermute_b32 v11, v129, v11
	ds_bpermute_b32 v16, v129, v16
	v_bitop3_b32 v9, s0, 15, v89 bitop3:0x48
	v_cmp_eq_u32_e64 s[0:1], 0, v9
	v_cndmask_b32_e64 v9, v13, v15, s[12:13]
	v_cndmask_b32_e64 v10, v14, v10, s[12:13]
	s_waitcnt lgkmcnt(1)
	v_add_f32_e32 v9, v9, v11
	s_waitcnt lgkmcnt(0)
	v_add_f32_e32 v10, v10, v16
	v_cndmask_b32_e64 v11, v9, v10, s[10:11]
	ds_bpermute_b32 v11, v128, v11
	v_cndmask_b32_e32 v12, v8, v21, vcc
	v_cndmask_b32_e64 v17, v21, v12, s[0:1]
	s_and_b64 s[0:1], s[0:1], vcc
	v_cndmask_b32_e64 v24, v28, v8, s[0:1]
	v_cndmask_b32_e64 v8, v10, v9, s[10:11]
	s_waitcnt lgkmcnt(0)
	v_add_f32_e32 v9, v8, v11
	ds_bpermute_b32 v14, v127, v9
	ds_bpermute_b32 v13, v137, v134
	ds_bpermute_b32 v8, v137, v133
	ds_bpermute_b32 v11, v137, v136
	ds_bpermute_b32 v10, v137, v135
	s_waitcnt lgkmcnt(4)
	v_add_f32_e32 v105, v9, v14
	ds_bpermute_b32 v9, v126, v105
	s_waitcnt lgkmcnt(4)
	v_mul_f32_e32 v12, v102, v13
	v_mul_f32_e32 v14, v88, v13
	s_waitcnt lgkmcnt(3)
	v_mul_f32_e32 v20, v100, v8
	v_pk_mul_f32 v[22:23], v[12:13], v[82:83] op_sel_hi:[0,1]
	v_pk_mul_f32 v[12:13], v[12:13], v[78:79] op_sel_hi:[0,1]
	v_pk_fma_f32 v[22:23], v[20:21], v[80:81], v[22:23] op_sel_hi:[0,1,1]
	v_pk_fma_f32 v[12:13], v[20:21], v[76:77], v[12:13] op_sel_hi:[0,1,1]
	s_waitcnt lgkmcnt(0)
	v_pk_add_f32 v[20:21], v[104:105], v[8:9]
	ds_bpermute_b32 v15, v125, v21
	v_mul_f32_e32 v18, v108, v11
	v_pk_mul_f32 v[8:9], v[104:105], v[8:9]
	v_mul_f32_e32 v16, v106, v10
	v_pk_fma_f32 v[4:5], v[110:111], v[4:5], v[12:13]
	v_pk_mul_f32 v[12:13], v[18:19], v[96:97] op_sel_hi:[0,1]
	v_mov_b32_e32 v9, v21
	v_pk_fma_f32 v[6:7], v[98:99], v[6:7], v[22:23]
	v_pk_fma_f32 v[12:13], v[16:17], v[92:93], v[12:13] op_sel_hi:[0,1,1]
	s_waitcnt lgkmcnt(0)
	v_pk_add_f32 v[8:9], v[8:9], v[14:15]
	v_pk_mul_f32 v[18:19], v[18:19], v[94:95] op_sel_hi:[0,1]
	v_pk_add_f32 v[6:7], v[6:7], v[12:13]
	ds_bpermute_b32 v12, v124, v9
	v_pk_fma_f32 v[18:19], v[16:17], v[90:91], v[18:19] op_sel_hi:[0,1,1]
	v_pk_add_f32 v[4:5], v[4:5], v[18:19]
	global_store_dwordx4 v[112:113], v[4:7], off nt
	s_add_i32 s0, s21, 4
	s_add_i32 s21, s21, 8
	v_mul_f32_e32 v4, v87, v11
	v_pk_fma_f32 v[4:5], v[86:87], v[10:11], v[4:5] op_sel_hi:[1,1,0]
	v_add_u32_e32 v137, 32, v137
	s_waitcnt lgkmcnt(0)
	v_mov_b32_e32 v5, v12
	v_pk_add_f32 v[4:5], v[8:9], v[4:5]
	s_nop 0
	v_fmac_f32_e32 v4, v131, v5
	v_bitop3_b32 v5, s0, 15, v89 bitop3:0x48
	v_cndmask_b32_e32 v6, v4, v17, vcc
	v_cmp_eq_u32_e64 s[0:1], 0, v5
	s_and_b64 vcc, s[0:1], vcc
	v_cndmask_b32_e32 v138, v24, v4, vcc
	v_cndmask_b32_e64 v139, v17, v6, s[0:1]
	s_mov_b64 s[0:1], 0x2000
	s_cmp_gt_u32 s22, 23
	v_lshl_add_u64 v[112:113], v[112:113], 0, s[0:1]
	s_cbranch_scc0 .LBB0_433
	v_or_b32_e32 v4, s91, v130
	v_lshlrev_b32_e32 v6, 11, v4
	v_mov_b32_e32 v7, v2
	v_lshl_add_u64 v[6:7], s[80:81], 0, v[6:7]
	s_lshl_b32 s0, s20, 1
	s_mov_b32 s1, s39
	v_and_b32_e32 v5, 15, v89
	v_lshl_add_u64 v[6:7], v[6:7], 0, s[0:1]
	v_lshl_add_u64 v[6:7], s[82:83], 1, v[6:7]
	v_lshlrev_b32_e32 v8, 1, v5
	v_mov_b32_e32 v9, v2
	v_lshl_add_u64 v[6:7], v[6:7], 0, v[8:9]
	s_mov_b64 s[0:1], 0x1926e000
	v_lshl_add_u64 v[8:9], v[6:7], 0, s[0:1]
	v_add_co_u32_e32 v6, vcc, 0x1926e000, v6
	s_cmp_lt_u32 s85, 64
	s_nop 0
	v_addc_co_u32_e32 v7, vcc, 0, v7, vcc
	v_cvt_pk_bf16_f32 v10, v138, v2
	global_store_short v[6:7], v10, off
	v_cvt_pk_bf16_f32 v6, v139, v2
	global_store_short v[8:9], v6, off offset:32
	s_cbranch_scc0 .LBB0_442
	s_lshl_b64 s[0:1], s[38:39], 10
	s_add_u32 s20, s60, s0
	s_addc_u32 s21, s61, s1
	v_lshlrev_b32_e32 v18, 2, v132
	v_mov_b32_e32 v99, v98
	s_add_u32 s0, s94, s0
	s_addc_u32 s1, s95, s1
	v_cmp_eq_u32_e32 vcc, 0, v5
	v_fma_f32 v10, v208, v109, 0
	v_fma_f32 v11, v208, v115, 0
	v_fma_f32 v12, v208, v117, 0
	v_fma_f32 v13, v208, v119, 0
	v_fmac_f32_e32 v10, v209, v107
	v_fmac_f32_e32 v11, v209, v114
	v_fmac_f32_e32 v12, v209, v116
	v_fmac_f32_e32 v13, v209, v118
	v_fmac_f32_e32 v10, v210, v70
	v_fmac_f32_e32 v11, v210, v72
	v_fmac_f32_e32 v12, v210, v74
	v_fmac_f32_e32 v13, v210, v84
	v_fmac_f32_e32 v10, v211, v71
	v_fmac_f32_e32 v11, v211, v73
	v_fmac_f32_e32 v12, v211, v75
	v_fmac_f32_e32 v13, v211, v85
	v_cndmask_b32_e64 v14, v12, v10, s[12:13]
	v_cndmask_b32_e64 v15, v13, v11, s[12:13]
	ds_bpermute_b32 v14, v129, v14
	ds_bpermute_b32 v15, v129, v15
	v_cndmask_b32_e64 v10, v10, v12, s[12:13]
	v_cndmask_b32_e64 v11, v11, v13, s[12:13]
	s_waitcnt lgkmcnt(1)
	v_add_f32_e32 v12, v10, v14
	s_waitcnt lgkmcnt(0)
	v_add_f32_e32 v13, v11, v15
	v_cndmask_b32_e64 v10, v12, v13, s[10:11]
	ds_bpermute_b32 v14, v128, v10
	v_cndmask_b32_e64 v12, v13, v12, s[10:11]
	v_pk_mul_f32 v[10:11], v[108:109], v[96:97] op_sel_hi:[0,1]
	v_pk_fma_f32 v[10:11], v[106:107], v[92:93], v[10:11] op_sel_hi:[0,1,1]
	s_waitcnt lgkmcnt(0)
	v_add_f32_e32 v16, v12, v14
	ds_bpermute_b32 v17, v127, v16
	v_pk_mul_f32 v[12:13], v[108:109], v[94:95] op_sel_hi:[0,1]
	v_pk_mul_f32 v[14:15], v[102:103], v[82:83] op_sel_hi:[0,1]
	v_pk_fma_f32 v[12:13], v[106:107], v[90:91], v[12:13] op_sel_hi:[0,1,1]
	v_pk_fma_f32 v[14:15], v[100:101], v[80:81], v[14:15] op_sel_hi:[0,1,1]
	s_waitcnt lgkmcnt(0)
	v_add_f32_e32 v19, v16, v17
	ds_bpermute_b32 v20, v126, v19
	v_pk_mul_f32 v[16:17], v[102:103], v[78:79] op_sel_hi:[0,1]
	v_pk_fma_f32 v[16:17], v[100:101], v[76:77], v[16:17] op_sel_hi:[0,1,1]
	v_pk_fma_f32 v[6:7], v[110:111], v[208:209], v[16:17]
	v_pk_fma_f32 v[14:15], v[98:99], v[210:211], v[14:15]
	s_waitcnt lgkmcnt(0)
	v_add_f32_e32 v19, v19, v20
	ds_bpermute_b32 v20, v125, v19
	v_pk_add_f32 v[8:9], v[12:13], v[6:7]
	v_pk_add_f32 v[10:11], v[10:11], v[14:15]
	global_store_dwordx4 v18, v[8:11], s[0:1]
	s_waitcnt lgkmcnt(0)
	v_add_f32_e32 v6, v19, v20
	ds_bpermute_b32 v7, v124, v6
	s_and_saveexec_b64 s[0:1], vcc
	s_cbranch_execz .LBB0_439
	v_cndmask_b32_e64 v5, v121, v122, s[4:5]
	v_cndmask_b32_e64 v5, v5, v123, s[6:7]
	v_mov_b32_e32 v105, v86
	v_mov_b32_e32 v89, v87
	v_cndmask_b32_e64 v10, v5, v120, s[8:9]
	v_pk_add_f32 v[8:9], v[104:105], v[88:89]
	s_waitcnt lgkmcnt(0)
	v_add_f32_e32 v5, v6, v7
	v_add_f32_e32 v8, v8, v9
	v_mul_f32_e32 v6, 0xbfb8aa3b, v10
	v_fmac_f32_e32 v8, v131, v5
	v_lshlrev_b32_e32 v4, 4, v4
	v_mov_b32_e32 v5, v2
	v_exp_f32_e32 v6, v6
	v_lshl_add_u64 v[4:5], s[80:81], 0, v[4:5]
	s_mov_b32 s85, s39
	v_lshl_add_u64 v[4:5], v[4:5], 0, s[84:85]
	v_add_co_u32_e32 v4, vcc, 0x272c000, v4
	v_max_f32_e64 v6, |v8|, v6
	s_nop 0
	v_addc_co_u32_e32 v5, vcc, 0, v5, vcc
	global_store_dword v[4:5], v6, off
